# v071 + FFN-up epilogue second load batch hoisted, LN (P21) gamma/beta in registers, final LN store-drain skip
# baseline (speedup 1.0000x reference)
.LBB0_1331:
	s_mov_b64 s[4:5], s[0:1]
	s_load_dword s4, s[4:5], 0xe8
	s_waitcnt lgkmcnt(0)
	s_cmp_gt_i32 s4, 21
	s_cbranch_scc1 .LBB0_1340
	s_mov_b64 s[4:5], s[0:1]
	s_load_dword s4, s[4:5], 0xec
	s_waitcnt lgkmcnt(0)
	s_cmp_lt_i32 s4, 22
	s_cbranch_scc1 .LBB0_1340
	s_mov_b64 s[4:5], s[0:1]
	s_mov_b64 s[6:7], s[0:1]
	s_mov_b64 s[14:15], s[0:1]
	s_mov_b64 s[8:9], s[0:1]
	s_mov_b64 s[12:13], s[0:1]
	v_mov_b32_e32 v0, v190
	s_nop 0
	v_readfirstlane_b32 s10, v0
	s_ashr_i32 s18, s10, 6
	s_mov_b32 s10, s2
	s_lshl_b32 s19, s10, 3
	s_add_i32 s10, s19, s18
	s_cmpk_gt_i32 s10, 0x3fff
	s_cbranch_scc1 .LBB0_1340
	s_load_dwordx2 s[14:15], s[14:15], 0xc0
	s_nop 0
	s_load_dwordx2 s[22:23], s[6:7], 0xb8
	s_nop 0
	s_load_dwordx2 s[6:7], s[4:5], 0xe0
	s_waitcnt vmcnt(0)
	v_and_b32_e32 v6, 63, v0
	v_lshlrev_b32_e32 v0, 4, v6
	s_waitcnt lgkmcnt(0)
	s_add_u32 s4, s14, 0x2000
	s_addc_u32 s5, s15, 0
	s_add_u32 s14, s22, 0x2000
	s_addc_u32 s15, s23, 0
	s_ashr_i32 s11, s10, 31
	s_lshl_b64 s[22:23], s[10:11], 12
	s_add_u32 s26, s6, s22
	s_addc_u32 s27, s7, s23
	v_lshl_add_u64 v[2:3], s[26:27], 0, v[0:1]
	s_mov_b64 s[26:27], 0x20100000
	s_mov_b32 s21, 0x20100000
	v_lshl_add_u64 v[4:5], v[2:3], 0, s[26:27]
	v_add_co_u32_e32 v2, vcc, s21, v2
	global_load_dwordx4 v[26:29], v[4:5], off offset:1024
	global_load_dwordx4 v[22:25], v[4:5], off offset:2048
	global_load_dwordx4 v[18:21], v[4:5], off offset:3072
	v_addc_co_u32_e32 v3, vcc, 0, v3, vcc
	global_load_dwordx4 v[30:33], v[2:3], off
	s_load_dwordx2 s[26:27], s[8:9], 0xe0
	s_load_dwordx2 s[36:37], s[12:13], 0xe0
	v_and_b32_e32 v2, 64, v197
	v_xor_b32_e32 v4, 16, v197
	v_add_u32_e32 v10, 64, v2
	v_xor_b32_e32 v8, 32, v197
	v_cmp_lt_i32_e64 s[8:9], v4, v10
	v_lshlrev_b32_e32 v2, 5, v6
	v_mov_b32_e32 v3, v1
	v_cndmask_b32_e64 v11, v197, v4, s[8:9]
	v_cmp_lt_i32_e64 s[8:9], v8, v10
	v_mov_b32_e32 v5, v1
	v_mov_b32_e32 v7, v1
	v_mov_b32_e32 v9, v1
	v_cmp_eq_u32_e32 vcc, 0, v6
	v_cndmask_b32_e64 v10, v197, v8, s[8:9]
	v_or_b32_e32 v4, 0x800, v2
	v_or_b32_e32 v6, 0x1000, v2
	v_or_b32_e32 v8, 0x1800, v2
	s_waitcnt lgkmcnt(0)
	s_cmp_lg_u64 s[36:37], 0
	v_lshl_add_u64 v[34:35], s[4:5], 0, v[2:3]
	v_lshl_add_u64 v[36:37], s[4:5], 0, v[4:5]
	v_lshl_add_u64 v[38:39], s[4:5], 0, v[6:7]
	v_lshl_add_u64 v[40:41], s[4:5], 0, v[8:9]
	s_cselect_b64 s[4:5], -1, 0
	s_lshl_b64 s[8:9], s[10:11], 3
	s_and_b64 s[12:13], s[4:5], vcc
	v_lshl_add_u64 v[42:43], s[14:15], 0, v[2:3]
	v_lshl_add_u64 v[44:45], s[14:15], 0, v[4:5]
	v_lshl_add_u64 v[46:47], s[14:15], 0, v[6:7]
	v_lshl_add_u64 v[48:49], s[14:15], 0, v[8:9]
	global_load_dwordx4 v[86:89], v[34:35], off
	global_load_dwordx4 v[90:93], v[34:35], off offset:16
	global_load_dwordx4 v[94:97], v[42:43], off
	global_load_dwordx4 v[98:101], v[42:43], off offset:16
	global_load_dwordx4 v[102:105], v[36:37], off
	global_load_dwordx4 v[106:109], v[36:37], off offset:16
	global_load_dwordx4 v[110:113], v[44:45], off
	global_load_dwordx4 v[130:133], v[44:45], off offset:16
	global_load_dwordx4 v[134:137], v[38:39], off
	global_load_dwordx4 v[138:141], v[38:39], off offset:16
	global_load_dwordx4 v[142:145], v[46:47], off
	global_load_dwordx4 v[158:161], v[46:47], off offset:16
	global_load_dwordx4 v[162:165], v[40:41], off
	global_load_dwordx4 v[166:169], v[40:41], off offset:16
	global_load_dwordx4 v[170:173], v[48:49], off
	global_load_dwordx4 v[176:179], v[48:49], off offset:16
	s_add_u32 s14, s36, s8
	s_addc_u32 s15, s37, s9
	s_add_u32 s64, s26, s22
	s_addc_u32 s65, s27, s23
	s_add_i32 s4, s20, s18
	s_add_i32 s4, s4, s19
	s_ashr_i32 s5, s4, 31
	s_lshl_b64 s[4:5], s[4:5], 12
	v_lshlrev_b32_e32 v59, 2, v11
	v_lshlrev_b32_e32 v68, 2, v10
	s_add_u32 s68, s6, s4
	s_addc_u32 s69, s7, s5
	s_waitcnt vmcnt(0)
	v_mov_b64_e32 v[10:11], v[26:27]
	s_waitcnt vmcnt(2)
	v_mov_b64_e32 v[6:7], v[22:23]
	s_waitcnt vmcnt(1)
	v_mov_b64_e32 v[2:3], v[18:19]
	v_mov_b64_e32 v[4:5], v[20:21]
	v_mov_b64_e32 v[8:9], v[24:25]
	s_waitcnt vmcnt(0)
	v_mov_b64_e32 v[14:15], v[30:31]
	v_mov_b64_e32 v[12:13], v[28:29]
	v_mov_b64_e32 v[16:17], v[32:33]
	s_branch .LBB0_1336
.LBB0_1335:
	s_or_b64 exec, exec, s[4:5]
	v_pk_mul_f32 v[64:65], v[64:65], v[58:59] op_sel_hi:[1,0]
	v_pk_mul_f32 v[62:63], v[62:63], v[58:59] op_sel_hi:[1,0]
	v_pk_mul_f32 v[60:61], v[60:61], v[58:59] op_sel_hi:[1,0]
	v_pk_mul_f32 v[66:67], v[66:67], v[58:59] op_sel_hi:[1,0]
	v_pk_mul_f32 v[56:57], v[56:57], v[58:59] op_sel_hi:[1,0]
	v_pk_mul_f32 v[54:55], v[54:55], v[58:59] op_sel_hi:[1,0]
	v_pk_mul_f32 v[52:53], v[52:53], v[58:59] op_sel_hi:[1,0]
	v_pk_mul_f32 v[50:51], v[50:51], v[58:59] op_sel_hi:[1,0]
	v_pk_mul_f32 v[32:33], v[32:33], v[58:59] op_sel_hi:[1,0]
	v_pk_mul_f32 v[30:31], v[30:31], v[58:59] op_sel_hi:[1,0]
	v_pk_mul_f32 v[28:29], v[28:29], v[58:59] op_sel_hi:[1,0]
	v_pk_mul_f32 v[26:27], v[26:27], v[58:59] op_sel_hi:[1,0]
	s_add_u32 s14, s14, s56
	v_pk_mul_f32 v[24:25], v[24:25], v[58:59] op_sel_hi:[1,0]
	v_pk_mul_f32 v[22:23], v[22:23], v[58:59] op_sel_hi:[1,0]
	v_pk_mul_f32 v[20:21], v[20:21], v[58:59] op_sel_hi:[1,0]
	v_pk_mul_f32 v[18:19], v[18:19], v[58:59] op_sel_hi:[1,0]
	s_addc_u32 s15, s15, s57
	v_pk_fma_f32 v[72:73], v[62:63], v[100:101], v[92:93]
	v_pk_fma_f32 v[64:65], v[64:65], v[94:95], v[86:87]
	v_pk_fma_f32 v[62:63], v[60:61], v[98:99], v[90:91]
	v_cvt_pk_bf16_f32 v60, v64, v65
	v_lshl_add_u64 v[64:65], s[64:65], 0, v[0:1]
	v_pk_fma_f32 v[66:67], v[66:67], v[96:97], v[88:89]
	v_add_co_u32_e32 v78, vcc, s85, v64
	v_cvt_pk_bf16_f32 v61, v66, v67
	v_cvt_pk_bf16_f32 v62, v62, v63
	v_cvt_pk_bf16_f32 v63, v72, v73
	v_addc_co_u32_e32 v79, vcc, 0, v65, vcc
	global_store_dwordx4 v[78:79], v[60:63], off
	s_nop 1
	s_nop 0
	s_add_u32 s64, s64, s58
	s_addc_u32 s65, s65, s59
	s_add_u32 s68, s68, s58
	s_addc_u32 s69, s69, s59
	s_andn2_b64 vcc, exec, s[80:81]
	v_pk_fma_f32 v[62:63], v[52:53], v[132:133], v[108:109]
	v_pk_fma_f32 v[56:57], v[56:57], v[112:113], v[104:105]
	v_pk_fma_f32 v[54:55], v[54:55], v[110:111], v[102:103]
	v_pk_fma_f32 v[52:53], v[50:51], v[130:131], v[106:107]
	v_cvt_pk_bf16_f32 v50, v54, v55
	v_cvt_pk_bf16_f32 v51, v56, v57
	v_cvt_pk_bf16_f32 v52, v52, v53
	v_cvt_pk_bf16_f32 v53, v62, v63
	global_store_dwordx4 v[78:79], v[50:53], off offset:1024
	s_nop 1
	s_nop 0
	v_pk_fma_f32 v[52:53], v[28:29], v[160:161], v[140:141]
	v_pk_fma_f32 v[32:33], v[32:33], v[144:145], v[136:137]
	v_pk_fma_f32 v[30:31], v[30:31], v[142:143], v[134:135]
	v_pk_fma_f32 v[28:29], v[26:27], v[158:159], v[138:139]
	v_cvt_pk_bf16_f32 v26, v30, v31
	v_cvt_pk_bf16_f32 v27, v32, v33
	v_cvt_pk_bf16_f32 v28, v28, v29
	v_cvt_pk_bf16_f32 v29, v52, v53
	global_store_dwordx4 v[78:79], v[26:29], off offset:2048
	s_nop 1
	s_nop 0
	v_pk_fma_f32 v[28:29], v[20:21], v[178:179], v[168:169]
	v_pk_fma_f32 v[24:25], v[24:25], v[172:173], v[164:165]
	v_pk_fma_f32 v[22:23], v[22:23], v[170:171], v[162:163]
	v_pk_fma_f32 v[20:21], v[18:19], v[176:177], v[166:167]
	v_cvt_pk_bf16_f32 v18, v22, v23
	v_cvt_pk_bf16_f32 v19, v24, v25
	v_cvt_pk_bf16_f32 v20, v20, v21
	v_cvt_pk_bf16_f32 v21, v28, v29
	global_store_dwordx4 v[78:79], v[18:21], off offset:3072
	s_nop 1
	s_waitcnt vmcnt(4)
	v_mov_b64_e32 v[24:25], v[8:9]
	v_mov_b64_e32 v[28:29], v[12:13]
	v_mov_b64_e32 v[20:21], v[4:5]
	v_mov_b64_e32 v[32:33], v[16:17]
	v_mov_b64_e32 v[18:19], v[2:3]
	v_mov_b64_e32 v[22:23], v[6:7]
	v_mov_b64_e32 v[26:27], v[10:11]
	v_mov_b64_e32 v[30:31], v[14:15]
	s_cbranch_vccz .LBB0_1340

.LBB0_1420:
	s_add_u32 s44, s92, 0xfff80080
	s_addc_u32 s45, s93, -1
	s_add_i32 s52, 0, 0x10000
	v_add_u32_e32 v126, s52, v205
	ds_read_b128 v[114:117], v126
	ds_read_b128 v[118:121], v126 offset:1024
	ds_read_b128 v[122:125], v126 offset:2048
	ds_read_b128 v[126:129], v126 offset:3072
	s_cmp_eq_u32 s51, 28
	s_cselect_b32 s95, s6, s45
	s_cselect_b32 s94, s7, s44
	s_cselect_b32 s45, s18, s50
	s_cselect_b32 s44, s19, s49
	v_lshl_add_u64 v[188:189], s[92:93], 0, v[168:169]
	s_add_i32 m0, s37, 0xc000
	ds_read_b128 v[172:175], v206
	ds_read_b128 v[176:179], v206 offset:1024
	ds_read_b128 v[180:183], v206 offset:2048
	ds_read_b128 v[184:187], v206 offset:3072
	ds_read_b128 v[208:211], v206 offset:4096
	ds_read_b128 v[212:215], v206 offset:5120
	ds_read_b128 v[216:219], v206 offset:6144
	ds_read_b128 v[220:223], v206 offset:7168
	global_load_lds_dwordx4 v[188:189], off
	v_lshl_add_u64 v[188:189], s[92:93], 0, v[170:171]
	s_add_i32 m0, s37, 0xe000
	s_nop 0
	global_load_lds_dwordx4 v[188:189], off
	s_waitcnt lgkmcnt(8)
	s_barrier
	s_waitcnt lgkmcnt(0)
	s_setprio 1
	s_waitcnt lgkmcnt(0)
	v_mfma_f32_16x16x32_bf16 v[138:141], v[114:117], v[172:175], v[138:141]
	v_mfma_f32_16x16x32_bf16 v[58:61], v[122:125], v[172:175], v[58:61]
	v_mfma_f32_16x16x32_bf16 v[134:137], v[114:117], v[180:183], v[134:137]
	v_mfma_f32_16x16x32_bf16 v[54:57], v[122:125], v[180:183], v[54:57]
	v_mfma_f32_16x16x32_bf16 v[110:113], v[114:117], v[208:211], v[110:113]
	v_mfma_f32_16x16x32_bf16 v[46:49], v[122:125], v[208:211], v[46:49]
	v_mfma_f32_16x16x32_bf16 v[102:105], v[114:117], v[216:219], v[102:105]
	v_mfma_f32_16x16x32_bf16 v[38:41], v[122:125], v[216:219], v[38:41]
	v_mfma_f32_16x16x32_bf16 v[138:141], v[118:121], v[176:179], v[138:141]
	v_mfma_f32_16x16x32_bf16 v[58:61], v[126:129], v[176:179], v[58:61]
	v_mfma_f32_16x16x32_bf16 v[134:137], v[118:121], v[184:187], v[134:137]
	v_mfma_f32_16x16x32_bf16 v[54:57], v[126:129], v[184:187], v[54:57]
	v_mfma_f32_16x16x32_bf16 v[110:113], v[118:121], v[212:215], v[110:113]
	v_mfma_f32_16x16x32_bf16 v[46:49], v[126:129], v[212:215], v[46:49]
	v_mfma_f32_16x16x32_bf16 v[102:105], v[118:121], v[220:223], v[102:105]
	v_mfma_f32_16x16x32_bf16 v[38:41], v[126:129], v[220:223], v[38:41]
	s_setprio 0
	s_barrier
	s_add_i32 s54, 0, 0x14000
	v_add_u32_e32 v188, s54, v205
	s_add_i32 s52, s52, s23
	ds_read_b128 v[224:227], v188
	ds_read_b128 v[228:231], v188 offset:1024
	ds_read_b128 v[232:235], v188 offset:2048
	ds_read_b128 v[236:239], v188 offset:3072
	v_lshl_add_u64 v[188:189], s[44:45], 0, v[0:1]
	s_mov_b32 m0, s52
	v_lshl_add_u64 v[240:241], s[44:45], 0, v[158:159]
	global_load_lds_dwordx4 v[188:189], off
	s_add_i32 m0, s52, 0x2000
	s_nop 0
	global_load_lds_dwordx4 v[240:241], off
	s_barrier
	s_waitcnt lgkmcnt(0)
	s_setprio 1
	s_waitcnt lgkmcnt(0)
	v_mfma_f32_16x16x32_bf16 v[142:145], v[224:227], v[172:175], v[142:145]
	v_mfma_f32_16x16x32_bf16 v[62:65], v[232:235], v[172:175], v[62:65]
	v_mfma_f32_16x16x32_bf16 v[130:133], v[224:227], v[180:183], v[130:133]
	v_mfma_f32_16x16x32_bf16 v[50:53], v[232:235], v[180:183], v[50:53]
	v_mfma_f32_16x16x32_bf16 v[106:109], v[224:227], v[208:211], v[106:109]
	v_mfma_f32_16x16x32_bf16 v[42:45], v[232:235], v[208:211], v[42:45]
	v_mfma_f32_16x16x32_bf16 v[98:101], v[224:227], v[216:219], v[98:101]
	v_mfma_f32_16x16x32_bf16 v[34:37], v[232:235], v[216:219], v[34:37]
	v_mfma_f32_16x16x32_bf16 v[142:145], v[228:231], v[176:179], v[142:145]
	v_mfma_f32_16x16x32_bf16 v[62:65], v[236:239], v[176:179], v[62:65]
	v_mfma_f32_16x16x32_bf16 v[130:133], v[228:231], v[184:187], v[130:133]
	v_mfma_f32_16x16x32_bf16 v[50:53], v[236:239], v[184:187], v[50:53]
	v_mfma_f32_16x16x32_bf16 v[106:109], v[228:231], v[212:215], v[106:109]
	v_mfma_f32_16x16x32_bf16 v[42:45], v[236:239], v[212:215], v[42:45]
	v_mfma_f32_16x16x32_bf16 v[98:101], v[228:231], v[220:223], v[98:101]
	v_mfma_f32_16x16x32_bf16 v[34:37], v[236:239], v[220:223], v[34:37]
	s_setprio 0
	s_mov_b32 m0, s37
	v_lshl_add_u64 v[242:243], s[94:95], 0, v[162:163]
	s_barrier
	ds_read_b128 v[172:175], v206 offset:16384
	ds_read_b128 v[176:179], v206 offset:17408
	ds_read_b128 v[180:183], v206 offset:18432
	ds_read_b128 v[184:187], v206 offset:19456
	ds_read_b128 v[208:211], v206 offset:20480
	ds_read_b128 v[212:215], v206 offset:21504
	ds_read_b128 v[216:219], v206 offset:22528
	ds_read_b128 v[220:223], v206 offset:23552
	global_load_lds_dwordx4 v[242:243], off
	v_lshl_add_u64 v[244:245], s[94:95], 0, v[160:161]
	s_mov_b32 m0, s40
	s_nop 0
	global_load_lds_dwordx4 v[244:245], off
	s_barrier
	s_waitcnt lgkmcnt(0)
	s_setprio 1
	s_waitcnt lgkmcnt(0)
	v_mfma_f32_16x16x32_bf16 v[94:97], v[114:117], v[172:175], v[94:97]
	v_mfma_f32_16x16x32_bf16 v[30:33], v[122:125], v[172:175], v[30:33]
	v_mfma_f32_16x16x32_bf16 v[86:89], v[114:117], v[180:183], v[86:89]
	v_mfma_f32_16x16x32_bf16 v[22:25], v[122:125], v[180:183], v[22:25]
	v_mfma_f32_16x16x32_bf16 v[78:81], v[114:117], v[208:211], v[78:81]
	v_mfma_f32_16x16x32_bf16 v[14:17], v[122:125], v[208:211], v[14:17]
	v_mfma_f32_16x16x32_bf16 v[70:73], v[114:117], v[216:219], v[70:73]
	v_mfma_f32_16x16x32_bf16 v[6:9], v[122:125], v[216:219], v[6:9]
	v_mfma_f32_16x16x32_bf16 v[94:97], v[118:121], v[176:179], v[94:97]
	v_mfma_f32_16x16x32_bf16 v[30:33], v[126:129], v[176:179], v[30:33]
	v_mfma_f32_16x16x32_bf16 v[86:89], v[118:121], v[184:187], v[86:89]
	v_mfma_f32_16x16x32_bf16 v[22:25], v[126:129], v[184:187], v[22:25]
	v_mfma_f32_16x16x32_bf16 v[78:81], v[118:121], v[212:215], v[78:81]
	v_mfma_f32_16x16x32_bf16 v[14:17], v[126:129], v[212:215], v[14:17]
	v_mfma_f32_16x16x32_bf16 v[70:73], v[118:121], v[220:223], v[70:73]
	v_mfma_f32_16x16x32_bf16 v[6:9], v[126:129], v[220:223], v[6:9]
	s_setprio 0
	s_barrier
	s_add_u32 s52, s44, 0x80000
	s_addc_u32 s53, s45, 0
	s_add_i32 s54, s54, s23
	v_lshl_add_u64 v[114:115], s[52:53], 0, v[0:1]
	s_mov_b32 m0, s54
	s_nop 0
	global_load_lds_dwordx4 v[114:115], off
	v_lshl_add_u64 v[114:115], s[52:53], 0, v[158:159]
	s_add_i32 m0, s54, 0x2000
	s_nop 0
	global_load_lds_dwordx4 v[114:115], off
	s_waitcnt vmcnt(6)
	s_barrier
	s_setprio 1
	v_mfma_f32_16x16x32_bf16 v[90:93], v[224:227], v[172:175], v[90:93]
	v_mfma_f32_16x16x32_bf16 v[26:29], v[232:235], v[172:175], v[26:29]
	v_mfma_f32_16x16x32_bf16 v[82:85], v[224:227], v[180:183], v[82:85]
	v_mfma_f32_16x16x32_bf16 v[18:21], v[232:235], v[180:183], v[18:21]
	v_mfma_f32_16x16x32_bf16 v[74:77], v[224:227], v[208:211], v[74:77]
	v_mfma_f32_16x16x32_bf16 v[10:13], v[232:235], v[208:211], v[10:13]
	v_mfma_f32_16x16x32_bf16 v[66:69], v[224:227], v[216:219], v[66:69]
	v_mfma_f32_16x16x32_bf16 v[2:5], v[232:235], v[216:219], v[2:5]
	v_mfma_f32_16x16x32_bf16 v[90:93], v[228:231], v[176:179], v[90:93]
	v_mfma_f32_16x16x32_bf16 v[26:29], v[236:239], v[176:179], v[26:29]
	v_mfma_f32_16x16x32_bf16 v[82:85], v[228:231], v[184:187], v[82:85]
	v_mfma_f32_16x16x32_bf16 v[18:21], v[236:239], v[184:187], v[18:21]
	v_mfma_f32_16x16x32_bf16 v[74:77], v[228:231], v[212:215], v[74:77]
	v_mfma_f32_16x16x32_bf16 v[10:13], v[236:239], v[212:215], v[10:13]
	v_mfma_f32_16x16x32_bf16 v[66:69], v[228:231], v[220:223], v[66:69]
	v_mfma_f32_16x16x32_bf16 v[2:5], v[236:239], v[220:223], v[2:5]
	s_setprio 0
	s_add_i32 s54, 0, 0x18000
	v_add_u32_e32 v126, s54, v205
	s_barrier
	ds_read_b128 v[114:117], v126
	ds_read_b128 v[118:121], v126 offset:1024
	ds_read_b128 v[122:125], v126 offset:2048
	ds_read_b128 v[126:129], v126 offset:3072
	s_add_u32 s52, s94, 0x80000
	s_addc_u32 s53, s95, 0
	s_mov_b32 m0, s41
	v_lshl_add_u64 v[224:225], s[52:53], 0, v[162:163]
	ds_read_b128 v[172:175], v206 offset:32768
	ds_read_b128 v[176:179], v206 offset:33792
	ds_read_b128 v[180:183], v206 offset:34816
	ds_read_b128 v[184:187], v206 offset:35840
	ds_read_b128 v[208:211], v206 offset:36864
	ds_read_b128 v[212:215], v206 offset:37888
	ds_read_b128 v[216:219], v206 offset:38912
	ds_read_b128 v[220:223], v206 offset:39936
	global_load_lds_dwordx4 v[224:225], off
	v_lshl_add_u64 v[224:225], s[52:53], 0, v[160:161]
	s_mov_b32 m0, s42
	s_nop 0
	global_load_lds_dwordx4 v[224:225], off
	s_waitcnt lgkmcnt(8)
	s_barrier
	s_waitcnt lgkmcnt(0)
	s_setprio 1
	s_waitcnt lgkmcnt(0)
	v_mfma_f32_16x16x32_bf16 v[138:141], v[114:117], v[172:175], v[138:141]
	v_mfma_f32_16x16x32_bf16 v[58:61], v[122:125], v[172:175], v[58:61]
	v_mfma_f32_16x16x32_bf16 v[134:137], v[114:117], v[180:183], v[134:137]
	v_mfma_f32_16x16x32_bf16 v[54:57], v[122:125], v[180:183], v[54:57]
	v_mfma_f32_16x16x32_bf16 v[110:113], v[114:117], v[208:211], v[110:113]
	v_mfma_f32_16x16x32_bf16 v[46:49], v[122:125], v[208:211], v[46:49]
	v_mfma_f32_16x16x32_bf16 v[102:105], v[114:117], v[216:219], v[102:105]
	v_mfma_f32_16x16x32_bf16 v[38:41], v[122:125], v[216:219], v[38:41]
	v_mfma_f32_16x16x32_bf16 v[138:141], v[118:121], v[176:179], v[138:141]
	v_mfma_f32_16x16x32_bf16 v[58:61], v[126:129], v[176:179], v[58:61]
	v_mfma_f32_16x16x32_bf16 v[134:137], v[118:121], v[184:187], v[134:137]
	v_mfma_f32_16x16x32_bf16 v[54:57], v[126:129], v[184:187], v[54:57]
	v_mfma_f32_16x16x32_bf16 v[110:113], v[118:121], v[212:215], v[110:113]
	v_mfma_f32_16x16x32_bf16 v[46:49], v[126:129], v[212:215], v[46:49]
	v_mfma_f32_16x16x32_bf16 v[102:105], v[118:121], v[220:223], v[102:105]
	v_mfma_f32_16x16x32_bf16 v[38:41], v[126:129], v[220:223], v[38:41]
	s_setprio 0
	s_barrier
	s_add_i32 s52, 0, 0x1c000
	s_add_i32 s53, s54, s23
	v_add_u32_e32 v207, s52, v205
	v_lshl_add_u64 v[188:189], v[188:189], 0, s[62:63]
	s_mov_b32 m0, s53
	ds_read_b128 v[224:227], v207
	ds_read_b128 v[228:231], v207 offset:1024
	ds_read_b128 v[232:235], v207 offset:2048
	ds_read_b128 v[236:239], v207 offset:3072
	global_load_lds_dwordx4 v[188:189], off
	v_lshl_add_u64 v[188:189], v[240:241], 0, s[62:63]
	s_add_i32 m0, s53, 0x2000
	s_nop 0
	global_load_lds_dwordx4 v[188:189], off
	s_barrier
	s_waitcnt lgkmcnt(0)
	s_setprio 1
	s_waitcnt lgkmcnt(0)
	v_mfma_f32_16x16x32_bf16 v[142:145], v[224:227], v[172:175], v[142:145]
	v_mfma_f32_16x16x32_bf16 v[62:65], v[232:235], v[172:175], v[62:65]
	v_mfma_f32_16x16x32_bf16 v[130:133], v[224:227], v[180:183], v[130:133]
	v_mfma_f32_16x16x32_bf16 v[50:53], v[232:235], v[180:183], v[50:53]
	v_mfma_f32_16x16x32_bf16 v[106:109], v[224:227], v[208:211], v[106:109]
	v_mfma_f32_16x16x32_bf16 v[42:45], v[232:235], v[208:211], v[42:45]
	v_mfma_f32_16x16x32_bf16 v[98:101], v[224:227], v[216:219], v[98:101]
	v_mfma_f32_16x16x32_bf16 v[34:37], v[232:235], v[216:219], v[34:37]
	v_mfma_f32_16x16x32_bf16 v[142:145], v[228:231], v[176:179], v[142:145]
	v_mfma_f32_16x16x32_bf16 v[62:65], v[236:239], v[176:179], v[62:65]
	v_mfma_f32_16x16x32_bf16 v[130:133], v[228:231], v[184:187], v[130:133]
	v_mfma_f32_16x16x32_bf16 v[50:53], v[236:239], v[184:187], v[50:53]
	v_mfma_f32_16x16x32_bf16 v[106:109], v[228:231], v[212:215], v[106:109]
	v_mfma_f32_16x16x32_bf16 v[42:45], v[236:239], v[212:215], v[42:45]
	v_mfma_f32_16x16x32_bf16 v[98:101], v[228:231], v[220:223], v[98:101]
	v_mfma_f32_16x16x32_bf16 v[34:37], v[236:239], v[220:223], v[34:37]
	s_setprio 0
	s_mov_b32 m0, s46
	v_lshl_add_u64 v[188:189], v[242:243], 0, s[62:63]
	s_barrier
	ds_read_b128 v[172:175], v206 offset:49152
	ds_read_b128 v[176:179], v206 offset:50176
	ds_read_b128 v[180:183], v206 offset:51200
	ds_read_b128 v[184:187], v206 offset:52224
	ds_read_b128 v[208:211], v206 offset:53248
	ds_read_b128 v[212:215], v206 offset:54272
	ds_read_b128 v[216:219], v206 offset:55296
	ds_read_b128 v[220:223], v206 offset:56320
	global_load_lds_dwordx4 v[188:189], off
	v_lshl_add_u64 v[188:189], v[244:245], 0, s[62:63]
	s_mov_b32 m0, s47
	s_nop 0
	global_load_lds_dwordx4 v[188:189], off
	s_barrier
	s_waitcnt lgkmcnt(0)
	s_setprio 1
	s_waitcnt lgkmcnt(0)
	v_mfma_f32_16x16x32_bf16 v[94:97], v[114:117], v[172:175], v[94:97]
	v_mfma_f32_16x16x32_bf16 v[30:33], v[122:125], v[172:175], v[30:33]
	v_mfma_f32_16x16x32_bf16 v[86:89], v[114:117], v[180:183], v[86:89]
	v_mfma_f32_16x16x32_bf16 v[22:25], v[122:125], v[180:183], v[22:25]
	v_mfma_f32_16x16x32_bf16 v[78:81], v[114:117], v[208:211], v[78:81]
	v_mfma_f32_16x16x32_bf16 v[14:17], v[122:125], v[208:211], v[14:17]
	v_mfma_f32_16x16x32_bf16 v[70:73], v[114:117], v[216:219], v[70:73]
	v_mfma_f32_16x16x32_bf16 v[6:9], v[122:125], v[216:219], v[6:9]
	v_mfma_f32_16x16x32_bf16 v[94:97], v[118:121], v[176:179], v[94:97]
	v_mfma_f32_16x16x32_bf16 v[30:33], v[126:129], v[176:179], v[30:33]
	v_mfma_f32_16x16x32_bf16 v[86:89], v[118:121], v[184:187], v[86:89]
	v_mfma_f32_16x16x32_bf16 v[22:25], v[126:129], v[184:187], v[22:25]
	v_mfma_f32_16x16x32_bf16 v[78:81], v[118:121], v[212:215], v[78:81]
	v_mfma_f32_16x16x32_bf16 v[14:17], v[126:129], v[212:215], v[14:17]
	v_mfma_f32_16x16x32_bf16 v[70:73], v[118:121], v[220:223], v[70:73]
	v_mfma_f32_16x16x32_bf16 v[6:9], v[126:129], v[220:223], v[6:9]
	s_setprio 0
	s_barrier
	s_add_u32 s44, s44, 0x80080
	s_addc_u32 s45, s45, 0
	s_add_i32 s52, s52, s23
	v_lshl_add_u64 v[114:115], s[44:45], 0, v[0:1]
	s_mov_b32 m0, s52
	s_nop 0
	global_load_lds_dwordx4 v[114:115], off
	v_lshl_add_u64 v[114:115], s[44:45], 0, v[158:159]
	s_add_i32 m0, s52, 0x2000
	s_nop 0
	global_load_lds_dwordx4 v[114:115], off
	s_waitcnt vmcnt(6)
	s_barrier
	s_setprio 1
	v_mfma_f32_16x16x32_bf16 v[90:93], v[224:227], v[172:175], v[90:93]
	v_mfma_f32_16x16x32_bf16 v[26:29], v[232:235], v[172:175], v[26:29]
	v_mfma_f32_16x16x32_bf16 v[82:85], v[224:227], v[180:183], v[82:85]
	v_mfma_f32_16x16x32_bf16 v[18:21], v[232:235], v[180:183], v[18:21]
	v_mfma_f32_16x16x32_bf16 v[74:77], v[224:227], v[208:211], v[74:77]
	v_mfma_f32_16x16x32_bf16 v[10:13], v[232:235], v[208:211], v[10:13]
	v_mfma_f32_16x16x32_bf16 v[66:69], v[224:227], v[216:219], v[66:69]
	v_mfma_f32_16x16x32_bf16 v[2:5], v[232:235], v[216:219], v[2:5]
	v_mfma_f32_16x16x32_bf16 v[90:93], v[228:231], v[176:179], v[90:93]
	v_mfma_f32_16x16x32_bf16 v[26:29], v[236:239], v[176:179], v[26:29]
	v_mfma_f32_16x16x32_bf16 v[82:85], v[228:231], v[184:187], v[82:85]
	v_mfma_f32_16x16x32_bf16 v[18:21], v[236:239], v[184:187], v[18:21]
	v_mfma_f32_16x16x32_bf16 v[74:77], v[228:231], v[212:215], v[74:77]
	v_mfma_f32_16x16x32_bf16 v[10:13], v[236:239], v[212:215], v[10:13]
	v_mfma_f32_16x16x32_bf16 v[66:69], v[228:231], v[220:223], v[66:69]
	v_mfma_f32_16x16x32_bf16 v[2:5], v[236:239], v[220:223], v[2:5]
	s_setprio 0
	s_add_i32 s51, s51, 2
	s_add_u32 s92, s92, 0x100
	s_addc_u32 s93, s93, 0
	s_add_u32 s49, s49, 0x100
	s_addc_u32 s50, s50, 0
	s_cmp_gt_u32 s51, 29
	s_barrier
	s_cbranch_scc0 .LBB0_1420
	v_lshl_or_b32 v174, s5, 7, v167
	v_ashrrev_i32_e32 v175, 31, v174
	v_lshlrev_b64 v[180:181], 2, v[174:175]
	v_lshl_add_u64 v[176:177], s[76:77], 0, v[180:181]
	v_lshl_add_u64 v[118:119], s[82:83], 0, v[180:181]
	v_lshl_add_u64 v[120:121], s[84:85], 0, v[180:181]
	v_lshl_add_u64 v[178:179], s[80:81], 0, v[180:181]
	global_load_dwordx4 v[114:117], v[176:177], off
	global_load_dwordx4 v[220:223], v[176:177], off offset:16
	global_load_dwordx4 v[122:125], v[118:119], off
	global_load_dwordx4 v[224:227], v[118:119], off offset:16
	global_load_dwordx4 v[228:231], v[120:121], off offset:16
	global_load_dwordx4 v[118:121], v[120:121], off
	s_lshl_b32 s4, s4, 8
	global_load_dwordx4 v[126:129], v[178:179], off
	global_load_dwordx4 v[232:235], v[178:179], off offset:16
	s_and_b32 s4, s4, 0x3f00
	s_add_i32 s4, s4, s43
	v_or_b32_e32 v207, s4, v164
	v_lshl_add_u64 v[172:173], v[174:175], 1, s[78:79]
	v_mov_b32_dpp v186, v138 row_shr:1 row_mask:0xf bank_mask:0xf bound_ctrl:1
	v_mov_b32_dpp v188, v138 row_shr:2 row_mask:0xf bank_mask:0xf bound_ctrl:1
	v_mov_b32_dpp v187, v139 row_shr:1 row_mask:0xf bank_mask:0xf bound_ctrl:1
	v_mov_b32_dpp v189, v139 row_shr:2 row_mask:0xf bank_mask:0xf bound_ctrl:1
	v_mov_b32_dpp v182, v140 row_shr:1 row_mask:0xf bank_mask:0xf bound_ctrl:1
	v_mov_b32_dpp v184, v140 row_shr:2 row_mask:0xf bank_mask:0xf bound_ctrl:1
	v_mov_b32_dpp v183, v141 row_shr:1 row_mask:0xf bank_mask:0xf bound_ctrl:1
	v_mov_b32_dpp v185, v141 row_shr:2 row_mask:0xf bank_mask:0xf bound_ctrl:1
	s_and_saveexec_b64 s[6:7], s[10:11]
	s_xor_b64 s[6:7], exec, s[6:7]
	s_cbranch_execz .LBB0_1423
	s_waitcnt vmcnt(0)
	v_pk_fma_f32 v[188:189], v[114:115], v[188:189], v[126:127]
	v_pk_fma_f32 v[184:185], v[116:117], v[184:185], v[128:129]
	v_pk_fma_f32 v[186:187], v[122:123], v[186:187], v[188:189]
	v_pk_fma_f32 v[182:183], v[124:125], v[182:183], v[184:185]
	v_pk_fma_f32 v[186:187], v[138:139], v[118:119], v[186:187]
	v_pk_fma_f32 v[182:183], v[140:141], v[120:121], v[182:183]
	v_mul_f32_e32 v175, 0xbfb8aa3b, v186
	v_exp_f32_e32 v175, v175
	v_mul_f32_e32 v188, 0xbfb8aa3b, v187
	v_exp_f32_e32 v188, v188
	v_mul_f32_e32 v184, 0xbfb8aa3b, v183
	v_add_f32_e32 v175, 1.0, v175
	v_exp_f32_e32 v185, v184
	v_add_f32_e32 v189, 1.0, v188
	v_rcp_f32_e32 v188, v175
	v_mul_f32_e32 v175, 0xbfb8aa3b, v182
	v_exp_f32_e32 v175, v175
	v_rcp_f32_e32 v189, v189
	v_add_f32_e32 v175, 1.0, v175
	v_rcp_f32_e32 v184, v175
	v_add_f32_e32 v175, 1.0, v185
	v_rcp_f32_e32 v185, v175
	v_pk_mul_f32 v[186:187], v[186:187], v[188:189]
	v_pk_mul_f32 v[182:183], v[182:183], v[184:185]
	v_pk_mul_f32 v[186:187], v[142:143], v[186:187]
	v_pk_mul_f32 v[182:183], v[144:145], v[182:183]
	v_cvt_pk_bf16_f32 v184, v186, v187
	v_cvt_pk_bf16_f32 v185, v182, v183
	v_mad_i64_i32 v[182:183], s[18:19], v207, s39, v[172:173]
	global_store_dwordx2 v[182:183], v[184:185], off

.LBB0_1433:
	s_or_b64 exec, exec, s[4:5]
	v_or_b32_e32 v88, 4, v174
	v_ashrrev_i32_e32 v89, 31, v88
	v_lshlrev_b64 v[92:93], 2, v[88:89]
	v_lshl_add_u64 v[70:71], s[82:83], 0, v[92:93]
	v_lshl_add_u64 v[72:73], s[84:85], 0, v[92:93]
	v_mov_b32_dpp v104, v58 row_shr:1 row_mask:0xf bank_mask:0xf bound_ctrl:1
	v_mov_b32_dpp v108, v58 row_shr:2 row_mask:0xf bank_mask:0xf bound_ctrl:1
	v_mov_b32_dpp v105, v59 row_shr:1 row_mask:0xf bank_mask:0xf bound_ctrl:1
	v_mov_b32_dpp v109, v59 row_shr:2 row_mask:0xf bank_mask:0xf bound_ctrl:1
	v_mov_b32_dpp v94, v60 row_shr:1 row_mask:0xf bank_mask:0xf bound_ctrl:1
	v_mov_b32_dpp v96, v60 row_shr:2 row_mask:0xf bank_mask:0xf bound_ctrl:1
	v_mov_b32_dpp v95, v61 row_shr:1 row_mask:0xf bank_mask:0xf bound_ctrl:1
	v_mov_b32_dpp v97, v61 row_shr:2 row_mask:0xf bank_mask:0xf bound_ctrl:1
	s_and_saveexec_b64 s[4:5], s[10:11]
	s_xor_b64 s[6:7], exec, s[4:5]
	s_cbranch_execz .LBB0_1435
	v_pk_fma_f32 v[108:109], v[220:221], v[108:109], v[232:233]
	v_pk_fma_f32 v[96:97], v[222:223], v[96:97], v[234:235]
	v_pk_fma_f32 v[104:105], v[224:225], v[104:105], v[108:109]
	v_pk_fma_f32 v[94:95], v[226:227], v[94:95], v[96:97]
	v_pk_fma_f32 v[104:105], v[58:59], v[228:229], v[104:105]
	v_pk_fma_f32 v[94:95], v[60:61], v[230:231], v[94:95]
	v_mul_f32_e32 v108, 0xbfb8aa3b, v104
	v_mul_f32_e32 v109, 0xbfb8aa3b, v105
	v_mul_f32_e32 v96, 0xbfb8aa3b, v94
	v_mul_f32_e32 v97, 0xbfb8aa3b, v95
	v_exp_f32_e32 v108, v108
	v_exp_f32_e32 v109, v109
	v_exp_f32_e32 v96, v96
	v_exp_f32_e32 v97, v97
	v_add_f32_e32 v108, 1.0, v108
	v_add_f32_e32 v109, 1.0, v109
	v_add_f32_e32 v96, 1.0, v96
	v_add_f32_e32 v97, 1.0, v97
	v_rcp_f32_e32 v108, v108
	v_rcp_f32_e32 v109, v109
	v_rcp_f32_e32 v96, v96
	v_rcp_f32_e32 v97, v97
	v_pk_mul_f32 v[104:105], v[104:105], v[108:109]
	s_nop 0
	v_pk_mul_f32 v[104:105], v[62:63], v[104:105]
	v_pk_mul_f32 v[94:95], v[94:95], v[96:97]
	v_cvt_pk_bf16_f32 v96, v104, v105
	v_pk_mul_f32 v[94:95], v[64:65], v[94:95]
	s_nop 0
	v_cvt_pk_bf16_f32 v97, v94, v95
	v_mad_i64_i32 v[94:95], s[4:5], v207, s39, v[172:173]
	global_store_dwordx2 v[94:95], v[96:97], off offset:8

.LBB0_1437:
	s_or_b64 exec, exec, s[6:7]
	ds_bpermute_b32 v65, v145, v58
	ds_bpermute_b32 v96, v145, v59
	ds_bpermute_b32 v63, v144, v58
	ds_bpermute_b32 v94, v144, v59
	v_mov_b32_dpp v64, v54 row_shr:2 row_mask:0xf bank_mask:0xf bound_ctrl:1
	v_mov_b32_dpp v95, v55 row_shr:2 row_mask:0xf bank_mask:0xf bound_ctrl:1
	v_mov_b32_dpp v62, v54 row_shr:1 row_mask:0xf bank_mask:0xf bound_ctrl:1
	v_mov_b32_dpp v58, v55 row_shr:1 row_mask:0xf bank_mask:0xf bound_ctrl:1
	ds_bpermute_b32 v104, v144, v60
	ds_bpermute_b32 v108, v145, v60
	ds_bpermute_b32 v111, v144, v61
	ds_bpermute_b32 v113, v145, v61
	s_waitcnt lgkmcnt(6)
	v_cndmask_b32_e64 v61, v96, v95, s[10:11]
	v_cndmask_b32_e64 v60, v65, v64, s[10:11]
	s_waitcnt lgkmcnt(4)
	v_cndmask_b32_e64 v59, v58, v94, s[8:9]
	v_cndmask_b32_e64 v58, v62, v63, s[8:9]
	v_pk_fma_f32 v[60:61], v[220:221], v[60:61], v[232:233]
	v_mov_b32_dpp v105, v56 row_shr:2 row_mask:0xf bank_mask:0xf bound_ctrl:1
	v_pk_fma_f32 v[58:59], v[224:225], v[58:59], v[60:61]
	v_mov_b32_dpp v112, v57 row_shr:2 row_mask:0xf bank_mask:0xf bound_ctrl:1
	v_pk_fma_f32 v[58:59], v[54:55], v[228:229], v[58:59]
	v_mov_b32_dpp v97, v56 row_shr:1 row_mask:0xf bank_mask:0xf bound_ctrl:1
	v_mul_f32_e32 v60, 0xbfb8aa3b, v58
	v_mul_f32_e32 v61, 0xbfb8aa3b, v59
	v_exp_f32_e32 v60, v60
	v_exp_f32_e32 v61, v61
	v_mov_b32_dpp v109, v57 row_shr:1 row_mask:0xf bank_mask:0xf bound_ctrl:1
	ds_bpermute_b32 v64, v144, v57
	v_add_f32_e32 v60, 1.0, v60
	v_add_f32_e32 v61, 1.0, v61
	v_rcp_f32_e32 v60, v60
	v_rcp_f32_e32 v61, v61
	v_mov_b32_dpp v62, v48 row_shr:2 row_mask:0xf bank_mask:0xf bound_ctrl:1
	v_mov_b32_dpp v65, v49 row_shr:2 row_mask:0xf bank_mask:0xf bound_ctrl:1
	v_mov_b32_dpp v63, v49 row_shr:1 row_mask:0xf bank_mask:0xf bound_ctrl:1
	v_pk_mul_f32 v[58:59], v[58:59], v[60:61]
	s_waitcnt lgkmcnt(1)
	v_cndmask_b32_e64 v61, v113, v112, s[10:11]
	v_cndmask_b32_e64 v60, v108, v105, s[10:11]
	v_pk_mul_f32 v[50:51], v[50:51], v[58:59]
	v_cndmask_b32_e64 v59, v109, v111, s[8:9]
	v_cndmask_b32_e64 v58, v97, v104, s[8:9]
	v_pk_fma_f32 v[60:61], v[222:223], v[60:61], v[234:235]
	v_cvt_pk_bf16_f32 v50, v50, v51
	v_pk_fma_f32 v[58:59], v[226:227], v[58:59], v[60:61]
	s_nop 0
	v_pk_fma_f32 v[58:59], v[56:57], v[230:231], v[58:59]
	ds_bpermute_b32 v57, v145, v57
	v_mul_f32_e32 v60, 0xbfb8aa3b, v58
	v_mul_f32_e32 v61, 0xbfb8aa3b, v59
	v_exp_f32_e32 v60, v60
	v_exp_f32_e32 v61, v61
	v_add_f32_e32 v60, 1.0, v60
	v_add_f32_e32 v61, 1.0, v61
	v_rcp_f32_e32 v60, v60
	v_rcp_f32_e32 v61, v61
	s_nop 0
	v_pk_mul_f32 v[58:59], v[58:59], v[60:61]
	s_nop 0
	v_pk_mul_f32 v[52:53], v[52:53], v[58:59]
	v_mov_b32_dpp v58, v46 row_shr:2 row_mask:0xf bank_mask:0xf bound_ctrl:1
	v_cvt_pk_bf16_f32 v51, v52, v53
	ds_bpermute_b32 v52, v144, v54
	ds_bpermute_b32 v54, v145, v54
	ds_bpermute_b32 v53, v144, v55
	ds_bpermute_b32 v55, v145, v55
	global_store_dwordx2 v[130:131], v[50:51], off offset:8
	v_mov_b32_dpp v50, v46 row_shr:1 row_mask:0xf bank_mask:0xf bound_ctrl:1
	v_mov_b32_dpp v51, v47 row_shr:1 row_mask:0xf bank_mask:0xf bound_ctrl:1
	v_mov_b32_dpp v59, v47 row_shr:2 row_mask:0xf bank_mask:0xf bound_ctrl:1
	s_waitcnt lgkmcnt(1)
	v_cndmask_b32_e64 v51, v51, v53, s[8:9]
	v_cndmask_b32_e64 v50, v50, v52, s[8:9]
	s_waitcnt lgkmcnt(0)
	v_cndmask_b32_e64 v53, v55, v59, s[10:11]
	v_cndmask_b32_e64 v52, v54, v58, s[10:11]
	v_pk_fma_f32 v[52:53], v[220:221], v[52:53], v[232:233]
	ds_bpermute_b32 v61, v144, v56
	v_pk_fma_f32 v[50:51], v[224:225], v[50:51], v[52:53]
	ds_bpermute_b32 v56, v145, v56
	v_pk_fma_f32 v[50:51], v[46:47], v[228:229], v[50:51]
	v_mov_b32_dpp v60, v48 row_shr:1 row_mask:0xf bank_mask:0xf bound_ctrl:1
	v_mul_f32_e32 v52, 0xbfb8aa3b, v50
	v_mul_f32_e32 v53, 0xbfb8aa3b, v51
	v_exp_f32_e32 v52, v52
	v_exp_f32_e32 v53, v53
	v_mov_b32_dpp v54, v40 row_shr:2 row_mask:0xf bank_mask:0xf bound_ctrl:1
	v_mov_b32_dpp v55, v41 row_shr:1 row_mask:0xf bank_mask:0xf bound_ctrl:1
	v_add_f32_e32 v52, 1.0, v52
	v_add_f32_e32 v53, 1.0, v53
	v_rcp_f32_e32 v52, v52
	v_rcp_f32_e32 v53, v53
	s_nop 0
	v_pk_mul_f32 v[50:51], v[50:51], v[52:53]
	v_cndmask_b32_e64 v53, v57, v65, s[10:11]
	s_waitcnt lgkmcnt(0)
	v_cndmask_b32_e64 v52, v56, v62, s[10:11]
	v_pk_mul_f32 v[42:43], v[42:43], v[50:51]
	v_cndmask_b32_e64 v51, v63, v64, s[8:9]
	v_cndmask_b32_e64 v50, v60, v61, s[8:9]
	v_pk_fma_f32 v[52:53], v[222:223], v[52:53], v[234:235]
	v_cvt_pk_bf16_f32 v42, v42, v43
	v_pk_fma_f32 v[50:51], v[226:227], v[50:51], v[52:53]
	ds_bpermute_b32 v56, v144, v49
	v_pk_fma_f32 v[50:51], v[48:49], v[230:231], v[50:51]
	ds_bpermute_b32 v49, v145, v49
	v_mul_f32_e32 v52, 0xbfb8aa3b, v50
	v_mul_f32_e32 v53, 0xbfb8aa3b, v51
	v_exp_f32_e32 v52, v52
	v_exp_f32_e32 v53, v53
	v_mov_b32_dpp v57, v41 row_shr:2 row_mask:0xf bank_mask:0xf bound_ctrl:1
	v_add_f32_e32 v52, 1.0, v52
	v_add_f32_e32 v53, 1.0, v53
	v_rcp_f32_e32 v52, v52
	v_rcp_f32_e32 v53, v53
	s_nop 0
	v_pk_mul_f32 v[50:51], v[50:51], v[52:53]
	s_nop 0
	v_pk_mul_f32 v[44:45], v[44:45], v[50:51]
	v_mov_b32_dpp v50, v38 row_shr:2 row_mask:0xf bank_mask:0xf bound_ctrl:1
	v_cvt_pk_bf16_f32 v43, v44, v45
	ds_bpermute_b32 v44, v144, v46
	ds_bpermute_b32 v46, v145, v46
	ds_bpermute_b32 v45, v144, v47
	ds_bpermute_b32 v47, v145, v47
	global_store_dwordx2 v[106:107], v[42:43], off offset:8
	v_mov_b32_dpp v42, v38 row_shr:1 row_mask:0xf bank_mask:0xf bound_ctrl:1
	v_mov_b32_dpp v43, v39 row_shr:1 row_mask:0xf bank_mask:0xf bound_ctrl:1
	v_mov_b32_dpp v51, v39 row_shr:2 row_mask:0xf bank_mask:0xf bound_ctrl:1
	s_waitcnt lgkmcnt(1)
	v_cndmask_b32_e64 v43, v43, v45, s[8:9]
	v_cndmask_b32_e64 v42, v42, v44, s[8:9]
	s_waitcnt lgkmcnt(0)
	v_cndmask_b32_e64 v45, v47, v51, s[10:11]
	v_cndmask_b32_e64 v44, v46, v50, s[10:11]
	v_pk_fma_f32 v[44:45], v[220:221], v[44:45], v[232:233]
	ds_bpermute_b32 v53, v144, v48
	v_pk_fma_f32 v[42:43], v[224:225], v[42:43], v[44:45]
	ds_bpermute_b32 v48, v145, v48
	v_pk_fma_f32 v[42:43], v[38:39], v[228:229], v[42:43]
	v_mov_b32_dpp v52, v40 row_shr:1 row_mask:0xf bank_mask:0xf bound_ctrl:1
	v_mul_f32_e32 v44, 0xbfb8aa3b, v42
	v_mul_f32_e32 v45, 0xbfb8aa3b, v43
	v_exp_f32_e32 v44, v44
	v_exp_f32_e32 v45, v45
	v_add_f32_e32 v44, 1.0, v44
	v_add_f32_e32 v45, 1.0, v45
	v_rcp_f32_e32 v44, v44
	v_rcp_f32_e32 v45, v45
	s_nop 0
	v_pk_mul_f32 v[42:43], v[42:43], v[44:45]
	v_cndmask_b32_e64 v45, v49, v57, s[10:11]
	s_waitcnt lgkmcnt(0)
	v_cndmask_b32_e64 v44, v48, v54, s[10:11]
	v_pk_mul_f32 v[34:35], v[34:35], v[42:43]
	v_cndmask_b32_e64 v43, v55, v56, s[8:9]
	v_cndmask_b32_e64 v42, v52, v53, s[8:9]
	v_pk_fma_f32 v[44:45], v[222:223], v[44:45], v[234:235]
	v_cvt_pk_bf16_f32 v34, v34, v35
	v_pk_fma_f32 v[42:43], v[226:227], v[42:43], v[44:45]
	s_nop 0
	v_pk_fma_f32 v[42:43], v[40:41], v[230:231], v[42:43]
	s_nop 0
	v_mul_f32_e32 v44, 0xbfb8aa3b, v42
	v_mul_f32_e32 v45, 0xbfb8aa3b, v43
	v_exp_f32_e32 v44, v44
	v_exp_f32_e32 v45, v45
	v_add_f32_e32 v44, 1.0, v44
	v_add_f32_e32 v45, 1.0, v45
	v_rcp_f32_e32 v44, v44
	v_rcp_f32_e32 v45, v45
	s_nop 0
	v_pk_mul_f32 v[42:43], v[42:43], v[44:45]
	s_nop 0
	v_pk_mul_f32 v[36:37], v[36:37], v[42:43]
	s_nop 0
	v_cvt_pk_bf16_f32 v35, v36, v37
	global_store_dwordx2 v[98:99], v[34:35], off offset:8
	s_and_saveexec_b64 s[4:5], s[12:13]
	s_cbranch_execz .LBB0_1439
	v_lshl_add_u64 v[34:35], s[64:65], 0, v[142:143]
	v_lshl_add_u64 v[34:35], v[88:89], 2, v[34:35]
	global_store_dwordx4 v[34:35], v[38:41], off
.LBB0_1439:
	s_or_b64 exec, exec, s[4:5]
	s_nop 0
	v_mov_b32_dpp v38, v30 row_shr:1 row_mask:0xf bank_mask:0xf bound_ctrl:1
	v_mov_b32_dpp v40, v30 row_shr:2 row_mask:0xf bank_mask:0xf bound_ctrl:1
	v_mov_b32_dpp v39, v31 row_shr:1 row_mask:0xf bank_mask:0xf bound_ctrl:1
	v_mov_b32_dpp v41, v31 row_shr:2 row_mask:0xf bank_mask:0xf bound_ctrl:1
	v_mov_b32_dpp v34, v32 row_shr:1 row_mask:0xf bank_mask:0xf bound_ctrl:1
	v_mov_b32_dpp v36, v32 row_shr:2 row_mask:0xf bank_mask:0xf bound_ctrl:1
	v_mov_b32_dpp v35, v33 row_shr:1 row_mask:0xf bank_mask:0xf bound_ctrl:1
	v_mov_b32_dpp v37, v33 row_shr:2 row_mask:0xf bank_mask:0xf bound_ctrl:1
	s_and_saveexec_b64 s[4:5], s[10:11]
	s_xor_b64 s[6:7], exec, s[4:5]
	s_cbranch_execz .LBB0_1441
	v_pk_fma_f32 v[40:41], v[220:221], v[40:41], v[232:233]
	v_pk_fma_f32 v[36:37], v[222:223], v[36:37], v[234:235]
	v_pk_fma_f32 v[38:39], v[224:225], v[38:39], v[40:41]
	v_pk_fma_f32 v[34:35], v[226:227], v[34:35], v[36:37]
	v_pk_fma_f32 v[38:39], v[30:31], v[228:229], v[38:39]
	v_pk_fma_f32 v[34:35], v[32:33], v[230:231], v[34:35]
	v_mul_f32_e32 v40, 0xbfb8aa3b, v38
	v_mul_f32_e32 v41, 0xbfb8aa3b, v39
	v_mul_f32_e32 v36, 0xbfb8aa3b, v34
	v_mul_f32_e32 v37, 0xbfb8aa3b, v35
	v_exp_f32_e32 v40, v40
	v_exp_f32_e32 v41, v41
	v_exp_f32_e32 v36, v36
	v_exp_f32_e32 v37, v37
	v_add_f32_e32 v40, 1.0, v40
	v_add_f32_e32 v41, 1.0, v41
	v_add_f32_e32 v36, 1.0, v36
	v_add_f32_e32 v37, 1.0, v37
	v_rcp_f32_e32 v40, v40
	v_rcp_f32_e32 v41, v41
	v_rcp_f32_e32 v36, v36
	v_rcp_f32_e32 v37, v37
	v_pk_mul_f32 v[38:39], v[38:39], v[40:41]
	s_nop 0
	v_pk_mul_f32 v[38:39], v[26:27], v[38:39]
	v_pk_mul_f32 v[34:35], v[34:35], v[36:37]
	v_cvt_pk_bf16_f32 v36, v38, v39
	v_pk_mul_f32 v[34:35], v[28:29], v[34:35]
	s_nop 0
	v_cvt_pk_bf16_f32 v37, v34, v35
	v_mad_i64_i32 v[34:35], s[4:5], v110, s39, v[172:173]
	global_store_dwordx2 v[34:35], v[36:37], off offset:8

.LBB0_1443:
	s_or_b64 exec, exec, s[4:5]
	ds_bpermute_b32 v28, v144, v30
	ds_bpermute_b32 v30, v145, v30
	ds_bpermute_b32 v29, v144, v31
	ds_bpermute_b32 v31, v145, v31
	v_mov_b32_dpp v26, v22 row_shr:1 row_mask:0xf bank_mask:0xf bound_ctrl:1
	v_mov_b32_dpp v34, v22 row_shr:2 row_mask:0xf bank_mask:0xf bound_ctrl:1
	v_mov_b32_dpp v27, v23 row_shr:1 row_mask:0xf bank_mask:0xf bound_ctrl:1
	v_mov_b32_dpp v35, v23 row_shr:2 row_mask:0xf bank_mask:0xf bound_ctrl:1
	s_waitcnt lgkmcnt(1)
	v_cndmask_b32_e64 v27, v27, v29, s[8:9]
	v_cndmask_b32_e64 v26, v26, v28, s[8:9]
	s_waitcnt lgkmcnt(0)
	v_cndmask_b32_e64 v29, v31, v35, s[10:11]
	v_cndmask_b32_e64 v28, v30, v34, s[10:11]
	v_pk_fma_f32 v[28:29], v[220:221], v[28:29], v[232:233]
	ds_bpermute_b32 v37, v144, v32
	v_pk_fma_f32 v[26:27], v[224:225], v[26:27], v[28:29]
	ds_bpermute_b32 v32, v145, v32
	v_pk_fma_f32 v[26:27], v[22:23], v[228:229], v[26:27]
	ds_bpermute_b32 v40, v144, v33
	v_mul_f32_e32 v28, 0xbfb8aa3b, v26
	v_mul_f32_e32 v29, 0xbfb8aa3b, v27
	v_exp_f32_e32 v28, v28
	v_exp_f32_e32 v29, v29
	ds_bpermute_b32 v33, v145, v33
	v_mov_b32_dpp v38, v24 row_shr:2 row_mask:0xf bank_mask:0xf bound_ctrl:1
	v_add_f32_e32 v28, 1.0, v28
	v_add_f32_e32 v29, 1.0, v29
	v_rcp_f32_e32 v28, v28
	v_rcp_f32_e32 v29, v29
	v_mov_b32_dpp v41, v25 row_shr:2 row_mask:0xf bank_mask:0xf bound_ctrl:1
	v_mov_b32_dpp v36, v24 row_shr:1 row_mask:0xf bank_mask:0xf bound_ctrl:1
	v_mov_b32_dpp v39, v25 row_shr:1 row_mask:0xf bank_mask:0xf bound_ctrl:1
	v_pk_mul_f32 v[26:27], v[26:27], v[28:29]
	s_waitcnt lgkmcnt(0)
	v_cndmask_b32_e64 v29, v33, v41, s[10:11]
	v_cndmask_b32_e64 v28, v32, v38, s[10:11]
	v_pk_mul_f32 v[18:19], v[18:19], v[26:27]
	v_cndmask_b32_e64 v27, v39, v40, s[8:9]
	v_cndmask_b32_e64 v26, v36, v37, s[8:9]
	v_pk_fma_f32 v[28:29], v[222:223], v[28:29], v[234:235]
	v_cvt_pk_bf16_f32 v18, v18, v19
	v_pk_fma_f32 v[26:27], v[226:227], v[26:27], v[28:29]
	ds_bpermute_b32 v32, v144, v25
	v_pk_fma_f32 v[26:27], v[24:25], v[230:231], v[26:27]
	ds_bpermute_b32 v25, v145, v25
	v_mul_f32_e32 v28, 0xbfb8aa3b, v26
	v_mul_f32_e32 v29, 0xbfb8aa3b, v27
	v_exp_f32_e32 v28, v28
	v_exp_f32_e32 v29, v29
	v_mov_b32_dpp v30, v16 row_shr:2 row_mask:0xf bank_mask:0xf bound_ctrl:1
	v_mov_b32_dpp v33, v17 row_shr:2 row_mask:0xf bank_mask:0xf bound_ctrl:1
	v_add_f32_e32 v28, 1.0, v28
	v_add_f32_e32 v29, 1.0, v29
	v_rcp_f32_e32 v28, v28
	v_rcp_f32_e32 v29, v29
	v_mov_b32_dpp v31, v17 row_shr:1 row_mask:0xf bank_mask:0xf bound_ctrl:1
	v_pk_mul_f32 v[26:27], v[26:27], v[28:29]
	s_nop 0
	v_pk_mul_f32 v[20:21], v[20:21], v[26:27]
	v_mov_b32_dpp v26, v14 row_shr:2 row_mask:0xf bank_mask:0xf bound_ctrl:1
	v_cvt_pk_bf16_f32 v19, v20, v21
	ds_bpermute_b32 v20, v144, v22
	ds_bpermute_b32 v22, v145, v22
	ds_bpermute_b32 v21, v144, v23
	ds_bpermute_b32 v23, v145, v23
	global_store_dwordx2 v[82:83], v[18:19], off offset:8
	v_mov_b32_dpp v18, v14 row_shr:1 row_mask:0xf bank_mask:0xf bound_ctrl:1
	v_mov_b32_dpp v19, v15 row_shr:1 row_mask:0xf bank_mask:0xf bound_ctrl:1
	v_mov_b32_dpp v27, v15 row_shr:2 row_mask:0xf bank_mask:0xf bound_ctrl:1
	s_waitcnt lgkmcnt(1)
	v_cndmask_b32_e64 v19, v19, v21, s[8:9]
	v_cndmask_b32_e64 v18, v18, v20, s[8:9]
	s_waitcnt lgkmcnt(0)
	v_cndmask_b32_e64 v21, v23, v27, s[10:11]
	v_cndmask_b32_e64 v20, v22, v26, s[10:11]
	v_pk_fma_f32 v[20:21], v[220:221], v[20:21], v[232:233]
	ds_bpermute_b32 v29, v144, v24
	v_pk_fma_f32 v[18:19], v[224:225], v[18:19], v[20:21]
	ds_bpermute_b32 v24, v145, v24
	v_pk_fma_f32 v[18:19], v[14:15], v[228:229], v[18:19]
	v_mov_b32_dpp v28, v16 row_shr:1 row_mask:0xf bank_mask:0xf bound_ctrl:1
	v_mul_f32_e32 v20, 0xbfb8aa3b, v18
	v_mul_f32_e32 v21, 0xbfb8aa3b, v19
	v_exp_f32_e32 v20, v20
	v_exp_f32_e32 v21, v21
	v_mov_b32_dpp v22, v8 row_shr:2 row_mask:0xf bank_mask:0xf bound_ctrl:1
	v_mov_b32_dpp v23, v9 row_shr:1 row_mask:0xf bank_mask:0xf bound_ctrl:1
	v_add_f32_e32 v20, 1.0, v20
	v_add_f32_e32 v21, 1.0, v21
	v_rcp_f32_e32 v20, v20
	v_rcp_f32_e32 v21, v21
	s_nop 0
	v_pk_mul_f32 v[18:19], v[18:19], v[20:21]
	v_cndmask_b32_e64 v21, v25, v33, s[10:11]
	s_waitcnt lgkmcnt(0)
	v_cndmask_b32_e64 v20, v24, v30, s[10:11]
	v_pk_mul_f32 v[10:11], v[10:11], v[18:19]
	v_cndmask_b32_e64 v19, v31, v32, s[8:9]
	v_cndmask_b32_e64 v18, v28, v29, s[8:9]
	v_pk_fma_f32 v[20:21], v[222:223], v[20:21], v[234:235]
	v_cvt_pk_bf16_f32 v10, v10, v11
	v_pk_fma_f32 v[18:19], v[226:227], v[18:19], v[20:21]
	ds_bpermute_b32 v24, v144, v17
	v_pk_fma_f32 v[18:19], v[16:17], v[230:231], v[18:19]
	ds_bpermute_b32 v17, v145, v17
	v_mul_f32_e32 v20, 0xbfb8aa3b, v18
	v_mul_f32_e32 v21, 0xbfb8aa3b, v19
	v_exp_f32_e32 v20, v20
	v_exp_f32_e32 v21, v21
	v_mov_b32_dpp v25, v9 row_shr:2 row_mask:0xf bank_mask:0xf bound_ctrl:1
	v_add_f32_e32 v20, 1.0, v20
	v_add_f32_e32 v21, 1.0, v21
	v_rcp_f32_e32 v20, v20
	v_rcp_f32_e32 v21, v21
	s_nop 0
	v_pk_mul_f32 v[18:19], v[18:19], v[20:21]
	s_nop 0
	v_pk_mul_f32 v[12:13], v[12:13], v[18:19]
	v_mov_b32_dpp v18, v6 row_shr:2 row_mask:0xf bank_mask:0xf bound_ctrl:1
	v_cvt_pk_bf16_f32 v11, v12, v13
	ds_bpermute_b32 v12, v144, v14
	ds_bpermute_b32 v14, v145, v14
	ds_bpermute_b32 v13, v144, v15
	ds_bpermute_b32 v15, v145, v15
	global_store_dwordx2 v[84:85], v[10:11], off offset:8
	v_mov_b32_dpp v10, v6 row_shr:1 row_mask:0xf bank_mask:0xf bound_ctrl:1
	v_mov_b32_dpp v11, v7 row_shr:1 row_mask:0xf bank_mask:0xf bound_ctrl:1
	v_mov_b32_dpp v19, v7 row_shr:2 row_mask:0xf bank_mask:0xf bound_ctrl:1
	s_waitcnt lgkmcnt(1)
	v_cndmask_b32_e64 v11, v11, v13, s[8:9]
	v_cndmask_b32_e64 v10, v10, v12, s[8:9]
	s_waitcnt lgkmcnt(0)
	v_cndmask_b32_e64 v13, v15, v19, s[10:11]
	v_cndmask_b32_e64 v12, v14, v18, s[10:11]
	v_pk_fma_f32 v[12:13], v[220:221], v[12:13], v[232:233]
	ds_bpermute_b32 v21, v144, v16
	v_pk_fma_f32 v[10:11], v[224:225], v[10:11], v[12:13]
	ds_bpermute_b32 v16, v145, v16
	v_pk_fma_f32 v[10:11], v[6:7], v[228:229], v[10:11]
	v_mov_b32_dpp v20, v8 row_shr:1 row_mask:0xf bank_mask:0xf bound_ctrl:1
	v_mul_f32_e32 v12, 0xbfb8aa3b, v10
	v_mul_f32_e32 v13, 0xbfb8aa3b, v11
	v_exp_f32_e32 v12, v12
	v_exp_f32_e32 v13, v13
	v_add_f32_e32 v12, 1.0, v12
	v_add_f32_e32 v13, 1.0, v13
	v_rcp_f32_e32 v12, v12
	v_rcp_f32_e32 v13, v13
	s_nop 0
	v_pk_mul_f32 v[10:11], v[10:11], v[12:13]
	v_cndmask_b32_e64 v13, v17, v25, s[10:11]
	s_waitcnt lgkmcnt(0)
	v_cndmask_b32_e64 v12, v16, v22, s[10:11]
	v_pk_mul_f32 v[2:3], v[2:3], v[10:11]
	v_cndmask_b32_e64 v11, v23, v24, s[8:9]
	v_cndmask_b32_e64 v10, v20, v21, s[8:9]
	v_pk_fma_f32 v[12:13], v[222:223], v[12:13], v[234:235]
	v_cvt_pk_bf16_f32 v2, v2, v3
	v_pk_fma_f32 v[10:11], v[226:227], v[10:11], v[12:13]
	s_nop 0
	v_pk_fma_f32 v[10:11], v[8:9], v[230:231], v[10:11]
	s_nop 0
	v_mul_f32_e32 v12, 0xbfb8aa3b, v10
	v_mul_f32_e32 v13, 0xbfb8aa3b, v11
	v_exp_f32_e32 v12, v12
	v_exp_f32_e32 v13, v13
	v_add_f32_e32 v12, 1.0, v12
	v_add_f32_e32 v13, 1.0, v13
	v_rcp_f32_e32 v12, v12
	v_rcp_f32_e32 v13, v13
	s_nop 0
	v_pk_mul_f32 v[10:11], v[10:11], v[12:13]
	s_nop 0
	v_pk_mul_f32 v[4:5], v[4:5], v[10:11]
	s_nop 0
	v_cvt_pk_bf16_f32 v3, v4, v5
	global_store_dwordx2 v[86:87], v[2:3], off offset:8
	s_and_saveexec_b64 s[4:5], s[12:13]
	s_cbranch_execz .LBB0_1416
	v_lshl_add_u64 v[2:3], s[64:65], 0, v[90:91]
	v_lshl_add_u64 v[2:3], v[88:89], 2, v[2:3]
	global_store_dwordx4 v[2:3], v[6:9], off
	s_branch .LBB0_1416

.Lln24_rot:
	v_mov_b64_e32 v[20:21], v[4:5]
	v_mov_b64_e32 v[24:25], v[8:9]
	v_mov_b64_e32 v[28:29], v[12:13]
	v_mov_b64_e32 v[32:33], v[16:17]
	v_lshl_add_u64 v[50:51], v[50:51], 0, s[58:59]
	v_lshl_add_u64 v[52:53], v[52:53], 0, s[86:87]
	s_andn2_b64 vcc, exec, s[14:15]
	v_mov_b64_e32 v[18:19], v[2:3]
	v_mov_b64_e32 v[22:23], v[6:7]
	v_mov_b64_e32 v[26:27], v[10:11]
	v_mov_b64_e32 v[30:31], v[14:15]
	s_cbranch_vccz .LBB0_1701

.LBB0_1699:
	v_lshlrev_b32_e32 v64, 16, v30
	v_and_b32_e32 v65, 0xffff0000, v30
	v_lshlrev_b32_e32 v62, 16, v31
	v_and_b32_e32 v63, 0xffff0000, v31
	v_lshlrev_b32_e32 v66, 16, v32
	v_and_b32_e32 v67, 0xffff0000, v32
	v_lshlrev_b32_e32 v68, 16, v33
	v_and_b32_e32 v69, 0xffff0000, v33
	v_add_f32_e32 v0, v64, v65
	s_waitcnt lgkmcnt(0)
	v_add_f32_e32 v72, v62, v63
	v_add_f32_e32 v0, v0, v72
	v_add_f32_e32 v72, v66, v67
	v_add_f32_e32 v73, v68, v69
	v_lshlrev_b32_e32 v54, 16, v26
	v_and_b32_e32 v55, 0xffff0000, v26
	v_lshlrev_b32_e32 v56, 16, v27
	v_and_b32_e32 v57, 0xffff0000, v27
	v_add_f32_e32 v0, 0, v0
	v_add_f32_e32 v72, v72, v73
	v_add_f32_e32 v0, v72, v0
	v_add_f32_e32 v72, v54, v55
	v_add_f32_e32 v73, v56, v57
	v_lshlrev_b32_e32 v58, 16, v28
	v_and_b32_e32 v59, 0xffff0000, v28
	v_lshlrev_b32_e32 v60, 16, v29
	v_and_b32_e32 v61, 0xffff0000, v29
	v_add_f32_e32 v72, v72, v73
	v_add_f32_e32 v0, v72, v0
	v_add_f32_e32 v72, v58, v59
	v_add_f32_e32 v73, v60, v61
	v_lshlrev_b32_e32 v26, 16, v22
	v_and_b32_e32 v27, 0xffff0000, v22
	v_lshlrev_b32_e32 v28, 16, v23
	v_and_b32_e32 v29, 0xffff0000, v23
	v_add_f32_e32 v72, v72, v73
	v_add_f32_e32 v0, v72, v0
	v_add_f32_e32 v72, v26, v27
	v_add_f32_e32 v73, v28, v29
	v_lshlrev_b32_e32 v30, 16, v24
	v_and_b32_e32 v31, 0xffff0000, v24
	v_lshlrev_b32_e32 v32, 16, v25
	v_and_b32_e32 v33, 0xffff0000, v25
	v_add_f32_e32 v72, v72, v73
	v_add_f32_e32 v0, v72, v0
	v_add_f32_e32 v72, v30, v31
	v_add_f32_e32 v73, v32, v33
	v_lshlrev_b32_e32 v22, 16, v18
	v_and_b32_e32 v23, 0xffff0000, v18
	v_lshlrev_b32_e32 v18, 16, v19
	v_and_b32_e32 v19, 0xffff0000, v19
	v_add_f32_e32 v72, v72, v73
	v_add_f32_e32 v0, v72, v0
	v_add_f32_e32 v72, v22, v23
	v_add_f32_e32 v73, v18, v19
	v_lshlrev_b32_e32 v24, 16, v20
	v_and_b32_e32 v25, 0xffff0000, v20
	v_lshlrev_b32_e32 v20, 16, v21
	v_and_b32_e32 v21, 0xffff0000, v21
	v_add_f32_e32 v72, v72, v73
	v_add_f32_e32 v0, v72, v0
	v_add_f32_e32 v72, v24, v25
	v_add_f32_e32 v73, v20, v21
	v_add_f32_e32 v72, v72, v73
	v_add_f32_e32 v0, v72, v0
	s_andn2_b64 vcc, exec, s[12:13]
	s_nop 0
	v_add_f32_dpp v0, v0, v0 quad_perm:[1,0,3,2] row_mask:0xf bank_mask:0xf bound_ctrl:1
	s_nop 1
	v_add_f32_dpp v0, v0, v0 quad_perm:[2,3,0,1] row_mask:0xf bank_mask:0xf bound_ctrl:1
	s_nop 1
	v_add_f32_dpp v0, v0, v0 row_half_mirror row_mask:0xf bank_mask:0xf bound_ctrl:1
	s_nop 1
	v_add_f32_dpp v0, v0, v0 row_ror:8 row_mask:0xf bank_mask:0xf bound_ctrl:1
	ds_bpermute_b32 v72, v70, v0
	s_waitcnt lgkmcnt(0)
	v_add_f32_e32 v0, v0, v72
	ds_bpermute_b32 v72, v71, v0
	s_waitcnt lgkmcnt(0)
	v_add_f32_e32 v0, v0, v72
	v_fmac_f32_e32 v63, 0xba000000, v0
	v_fmac_f32_e32 v65, 0xba000000, v0
	v_fmac_f32_e32 v62, 0xba000000, v0
	v_fmac_f32_e32 v64, 0xba000000, v0
	v_mul_f32_e32 v72, v65, v65
	v_mul_f32_e32 v73, v63, v63
	v_fmac_f32_e32 v72, v64, v64
	v_fmac_f32_e32 v73, v62, v62
	v_fmac_f32_e32 v69, 0xba000000, v0
	v_fmac_f32_e32 v67, 0xba000000, v0
	v_add_f32_e32 v72, v72, v73
	v_fmac_f32_e32 v68, 0xba000000, v0
	v_fmac_f32_e32 v66, 0xba000000, v0
	v_mul_f32_e32 v73, v67, v67
	v_mul_f32_e32 v74, v69, v69
	v_fmac_f32_e32 v73, v66, v66
	v_fmac_f32_e32 v74, v68, v68
	v_add_f32_e32 v73, v73, v74
	v_fmac_f32_e32 v57, 0xba000000, v0
	v_fmac_f32_e32 v55, 0xba000000, v0
	v_add_f32_e32 v72, v72, v73
	v_fmac_f32_e32 v56, 0xba000000, v0
	v_fmac_f32_e32 v54, 0xba000000, v0
	v_mul_f32_e32 v73, v55, v55
	v_mul_f32_e32 v74, v57, v57
	v_fmac_f32_e32 v73, v54, v54
	v_fmac_f32_e32 v74, v56, v56
	v_add_f32_e32 v73, v73, v74
	v_fmac_f32_e32 v61, 0xba000000, v0
	v_fmac_f32_e32 v59, 0xba000000, v0
	v_add_f32_e32 v72, v73, v72
	v_fmac_f32_e32 v60, 0xba000000, v0
	v_fmac_f32_e32 v58, 0xba000000, v0
	v_mul_f32_e32 v73, v59, v59
	v_mul_f32_e32 v74, v61, v61
	v_fmac_f32_e32 v73, v58, v58
	v_fmac_f32_e32 v74, v60, v60
	v_add_f32_e32 v73, v73, v74
	v_fmac_f32_e32 v29, 0xba000000, v0
	v_fmac_f32_e32 v27, 0xba000000, v0
	v_add_f32_e32 v72, v73, v72
	v_fmac_f32_e32 v28, 0xba000000, v0
	v_fmac_f32_e32 v26, 0xba000000, v0
	v_mul_f32_e32 v73, v27, v27
	v_mul_f32_e32 v74, v29, v29
	v_fmac_f32_e32 v73, v26, v26
	v_fmac_f32_e32 v74, v28, v28
	v_add_f32_e32 v73, v73, v74
	v_fmac_f32_e32 v33, 0xba000000, v0
	v_fmac_f32_e32 v31, 0xba000000, v0
	v_add_f32_e32 v72, v73, v72
	v_fmac_f32_e32 v32, 0xba000000, v0
	v_fmac_f32_e32 v30, 0xba000000, v0
	v_mul_f32_e32 v73, v31, v31
	v_mul_f32_e32 v74, v33, v33
	v_fmac_f32_e32 v73, v30, v30
	v_fmac_f32_e32 v74, v32, v32
	v_add_f32_e32 v73, v73, v74
	v_fmac_f32_e32 v19, 0xba000000, v0
	v_fmac_f32_e32 v23, 0xba000000, v0
	v_add_f32_e32 v72, v73, v72
	v_fmac_f32_e32 v18, 0xba000000, v0
	v_fmac_f32_e32 v22, 0xba000000, v0
	v_mul_f32_e32 v73, v23, v23
	v_mul_f32_e32 v74, v19, v19
	v_fmac_f32_e32 v73, v22, v22
	v_fmac_f32_e32 v74, v18, v18
	v_add_f32_e32 v73, v73, v74
	v_fmac_f32_e32 v21, 0xba000000, v0
	v_fmac_f32_e32 v25, 0xba000000, v0
	v_add_f32_e32 v72, v73, v72
	v_fmac_f32_e32 v20, 0xba000000, v0
	v_fmac_f32_e32 v24, 0xba000000, v0
	v_mul_f32_e32 v0, v25, v25
	v_mul_f32_e32 v73, v21, v21
	v_fmac_f32_e32 v0, v24, v24
	v_fmac_f32_e32 v73, v20, v20
	v_add_f32_e32 v0, v0, v73
	v_add_f32_e32 v0, v0, v72
	s_nop 1
	v_add_f32_dpp v0, v0, v0 quad_perm:[1,0,3,2] row_mask:0xf bank_mask:0xf bound_ctrl:1
	s_nop 1
	v_add_f32_dpp v0, v0, v0 quad_perm:[2,3,0,1] row_mask:0xf bank_mask:0xf bound_ctrl:1
	s_nop 1
	v_add_f32_dpp v0, v0, v0 row_half_mirror row_mask:0xf bank_mask:0xf bound_ctrl:1
	s_nop 1
	v_add_f32_dpp v0, v0, v0 row_ror:8 row_mask:0xf bank_mask:0xf bound_ctrl:1
	ds_bpermute_b32 v72, v70, v0
	s_waitcnt lgkmcnt(0)
	v_add_f32_e32 v0, v0, v72
	ds_bpermute_b32 v72, v71, v0
	s_cbranch_vccnz .LBB0_1696
	global_load_dwordx4 v[74:77], v[34:35], off offset:16
	global_load_dwordx4 v[78:81], v[42:43], off offset:16
	global_load_dwordx4 v[82:85], v[42:43], off
	global_load_dwordx4 v[86:89], v[34:35], off
	s_waitcnt lgkmcnt(0)
	v_add_f32_e32 v0, v0, v72
	v_fmamk_f32 v0, v0, 0x3a000000, v198
	v_mul_f32_e32 v72, 0x4f800000, v0
	v_cmp_gt_f32_e32 vcc, s84, v0
	s_nop 1
	v_cndmask_b32_e32 v0, v0, v72, vcc
	v_sqrt_f32_e32 v72, v0
	s_nop 0
	v_add_u32_e32 v73, -1, v72
	v_add_u32_e32 v90, 1, v72
	v_fma_f32 v91, -v73, v72, v0
	v_fma_f32 v92, -v90, v72, v0
	v_cmp_ge_f32_e64 s[8:9], 0, v91
	s_nop 1
	v_cndmask_b32_e64 v72, v72, v73, s[8:9]
	v_cmp_lt_f32_e64 s[8:9], 0, v92
	s_nop 1
	v_cndmask_b32_e64 v72, v72, v90, s[8:9]
	v_mul_f32_e32 v73, 0x37800000, v72
	v_cndmask_b32_e32 v72, v72, v73, vcc
	v_cmp_class_f32_e32 vcc, v0, v199
	s_nop 1
	v_cndmask_b32_e32 v0, v72, v0, vcc
	v_div_scale_f32 v72, s[4:5], v0, v0, 1.0
	v_rcp_f32_e32 v73, v72
	v_div_scale_f32 v90, vcc, 1.0, v0, 1.0
	v_fma_f32 v91, -v72, v73, 1.0
	v_fmac_f32_e32 v73, v91, v73
	v_mul_f32_e32 v91, v90, v73
	v_fma_f32 v92, -v72, v91, v90
	v_fmac_f32_e32 v91, v92, v73
	v_fma_f32 v72, -v72, v91, v90
	v_div_fmas_f32 v72, v72, v73, v91
	v_div_fixup_f32 v0, v72, v0, 1.0
	v_pk_mul_f32 v[66:67], v[66:67], v[0:1] op_sel_hi:[1,0]
	v_pk_mul_f32 v[68:69], v[68:69], v[0:1] op_sel_hi:[1,0]
	v_pk_mul_f32 v[72:73], v[64:65], v[0:1] op_sel_hi:[1,0]
	v_pk_mul_f32 v[90:91], v[62:63], v[0:1] op_sel_hi:[1,0]
	v_pk_mul_f32 v[60:61], v[60:61], v[0:1] op_sel_hi:[1,0]
	v_pk_mul_f32 v[58:59], v[58:59], v[0:1] op_sel_hi:[1,0]
	v_pk_mul_f32 v[32:33], v[32:33], v[0:1] op_sel_hi:[1,0]
	v_pk_mul_f32 v[30:31], v[30:31], v[0:1] op_sel_hi:[1,0]
	v_pk_mul_f32 v[24:25], v[24:25], v[0:1] op_sel_hi:[1,0]
	v_pk_mul_f32 v[22:23], v[22:23], v[0:1] op_sel_hi:[1,0]
	v_pk_mul_f32 v[20:21], v[20:21], v[0:1] op_sel_hi:[1,0]
	s_waitcnt vmcnt(2)
	v_pk_fma_f32 v[64:65], v[68:69], v[80:81], v[76:77]
	v_pk_fma_f32 v[62:63], v[66:67], v[78:79], v[74:75]
	s_waitcnt vmcnt(0)
	v_pk_fma_f32 v[68:69], v[90:91], v[84:85], v[88:89]
	v_pk_fma_f32 v[66:67], v[72:73], v[82:83], v[86:87]
	global_store_dwordx4 v[52:53], v[66:69], off offset:-4096
	global_store_dwordx4 v[52:53], v[62:65], off offset:-4080
	global_load_dwordx4 v[62:65], v[36:37], off offset:16
	s_nop 0
	global_load_dwordx4 v[66:69], v[44:45], off offset:16
	global_load_dwordx4 v[72:75], v[44:45], off
	global_load_dwordx4 v[76:79], v[36:37], off
	v_pk_mul_f32 v[80:81], v[56:57], v[0:1] op_sel_hi:[1,0]
	v_pk_mul_f32 v[82:83], v[54:55], v[0:1] op_sel_hi:[1,0]
	s_waitcnt vmcnt(2)
	v_pk_fma_f32 v[54:55], v[58:59], v[66:67], v[62:63]
	v_pk_fma_f32 v[56:57], v[60:61], v[68:69], v[64:65]
	s_waitcnt vmcnt(0)
	v_pk_fma_f32 v[58:59], v[82:83], v[72:73], v[76:77]
	v_pk_fma_f32 v[60:61], v[80:81], v[74:75], v[78:79]
	global_store_dwordx4 v[52:53], v[58:61], off offset:-2048
	global_store_dwordx4 v[52:53], v[54:57], off offset:-2032
	global_load_dwordx4 v[54:57], v[38:39], off offset:16
	s_nop 0
	global_load_dwordx4 v[58:61], v[46:47], off offset:16
	global_load_dwordx4 v[62:65], v[46:47], off
	global_load_dwordx4 v[66:69], v[38:39], off
	v_pk_mul_f32 v[72:73], v[28:29], v[0:1] op_sel_hi:[1,0]
	v_pk_mul_f32 v[74:75], v[26:27], v[0:1] op_sel_hi:[1,0]
	s_waitcnt vmcnt(2)
	v_pk_fma_f32 v[26:27], v[30:31], v[58:59], v[54:55]
	v_pk_fma_f32 v[28:29], v[32:33], v[60:61], v[56:57]
	s_waitcnt vmcnt(0)
	v_pk_fma_f32 v[30:31], v[74:75], v[62:63], v[66:67]
	v_pk_fma_f32 v[32:33], v[72:73], v[64:65], v[68:69]
	global_store_dwordx4 v[52:53], v[30:33], off
	global_store_dwordx4 v[52:53], v[26:29], off offset:16
	global_load_dwordx4 v[26:29], v[40:41], off offset:16
	s_nop 0
	global_load_dwordx4 v[30:33], v[48:49], off offset:16
	global_load_dwordx4 v[54:57], v[48:49], off
	global_load_dwordx4 v[58:61], v[40:41], off
	v_pk_mul_f32 v[62:63], v[18:19], v[0:1] op_sel_hi:[1,0]
	s_waitcnt vmcnt(2)
	v_pk_fma_f32 v[18:19], v[24:25], v[30:31], v[26:27]
	v_pk_fma_f32 v[20:21], v[20:21], v[32:33], v[28:29]
	s_waitcnt vmcnt(0)
	v_pk_fma_f32 v[22:23], v[22:23], v[54:55], v[58:59]
	v_pk_fma_f32 v[24:25], v[62:63], v[56:57], v[60:61]
	global_store_dwordx4 v[52:53], v[22:25], off offset:2048
	global_store_dwordx4 v[52:53], v[18:21], off offset:2064
	s_nop 1
	s_branch .Lln24_rot
